# v056 with all six K-loop heads aligned to 64 bytes (p2align padding outside the loops)
# speedup vs baseline: 1.0065x; 1.0065x over previous
.LBB0_133:
	s_ashr_i32 s19, s18, 31
	s_lshl_b64 s[28:29], s[18:19], 19
	v_cmp_lt_i64_e32 vcc, s[62:63], v[182:183]
	s_add_u32 s62, s27, s28
	s_addc_u32 s63, s37, s29
	s_and_b64 s[28:29], vcc, exec
	s_cselect_b32 s5, s63, s67
	s_cselect_b32 s7, s62, s66
	s_ashr_i32 s17, s16, 31
	s_lshl_b64 s[28:29], s[16:17], 19
	s_add_u32 s64, s46, s28
	s_addc_u32 s65, s47, s29
	s_and_b64 s[28:29], vcc, exec
	s_cselect_b32 s17, s65, s69
	s_cselect_b32 s19, s64, s68
	s_add_u32 s66, s66, 0x40080
	s_addc_u32 s67, s67, 0
	s_add_u32 s85, s68, 0x100
	v_mov_b64_e32 v[0:1], 0
	v_mov_b64_e32 v[2:3], 0
	v_mov_b64_e32 v[4:5], 0
	v_mov_b64_e32 v[6:7], 0
	v_mov_b64_e32 v[8:9], 0
	v_mov_b64_e32 v[10:11], 0
	v_mov_b64_e32 v[12:13], 0
	v_mov_b64_e32 v[14:15], 0
	v_mov_b64_e32 v[16:17], 0
	v_mov_b64_e32 v[18:19], 0
	v_mov_b64_e32 v[20:21], 0
	v_mov_b64_e32 v[22:23], 0
	v_mov_b64_e32 v[24:25], 0
	v_mov_b64_e32 v[26:27], 0
	v_mov_b64_e32 v[28:29], 0
	v_mov_b64_e32 v[30:31], 0
	v_mov_b64_e32 v[32:33], 0
	v_mov_b64_e32 v[34:35], 0
	v_mov_b64_e32 v[36:37], 0
	v_mov_b64_e32 v[38:39], 0
	v_mov_b64_e32 v[40:41], 0
	v_mov_b64_e32 v[42:43], 0
	v_mov_b64_e32 v[44:45], 0
	v_mov_b64_e32 v[46:47], 0
	v_mov_b64_e32 v[48:49], 0
	v_mov_b64_e32 v[50:51], 0
	v_mov_b64_e32 v[52:53], 0
	v_mov_b64_e32 v[54:55], 0
	v_mov_b64_e32 v[56:57], 0
	v_mov_b64_e32 v[58:59], 0
	v_mov_b64_e32 v[60:61], 0
	v_mov_b64_e32 v[62:63], 0
	v_mov_b64_e32 v[64:65], 0
	v_mov_b64_e32 v[66:67], 0
	v_mov_b64_e32 v[68:69], 0
	v_mov_b64_e32 v[70:71], 0
	v_mov_b64_e32 v[72:73], 0
	v_mov_b64_e32 v[74:75], 0
	v_mov_b64_e32 v[76:77], 0
	v_mov_b64_e32 v[78:79], 0
	v_mov_b64_e32 v[80:81], 0
	v_mov_b64_e32 v[82:83], 0
	v_mov_b64_e32 v[84:85], 0
	v_mov_b64_e32 v[86:87], 0
	v_mov_b64_e32 v[88:89], 0
	v_mov_b64_e32 v[90:91], 0
	v_mov_b64_e32 v[92:93], 0
	v_mov_b64_e32 v[94:95], 0
	v_mov_b64_e32 v[96:97], 0
	v_mov_b64_e32 v[98:99], 0
	v_mov_b64_e32 v[100:101], 0
	v_mov_b64_e32 v[102:103], 0
	v_mov_b64_e32 v[104:105], 0
	v_mov_b64_e32 v[106:107], 0
	v_mov_b64_e32 v[108:109], 0
	v_mov_b64_e32 v[110:111], 0
	v_mov_b64_e32 v[112:113], 0
	v_mov_b64_e32 v[114:115], 0
	v_mov_b64_e32 v[116:117], 0
	v_mov_b64_e32 v[118:119], 0
	v_mov_b64_e32 v[120:121], 0
	v_mov_b64_e32 v[122:123], 0
	v_mov_b64_e32 v[124:125], 0
	v_mov_b64_e32 v[126:127], 0
	s_addc_u32 s91, s69, 0
	s_mov_b32 vcc_lo, -2
	s_waitcnt vmcnt(0)
	.p2alignl 6, 3212836864

.LBB0_412:
	s_add_i32 s13, s67, -2
	s_add_u32 s85, s62, 0x100
	v_mov_b64_e32 v[0:1], 0
	v_mov_b64_e32 v[2:3], 0
	v_mov_b64_e32 v[4:5], 0
	v_mov_b64_e32 v[6:7], 0
	v_mov_b64_e32 v[8:9], 0
	v_mov_b64_e32 v[10:11], 0
	v_mov_b64_e32 v[12:13], 0
	v_mov_b64_e32 v[14:15], 0
	v_mov_b64_e32 v[16:17], 0
	v_mov_b64_e32 v[18:19], 0
	v_mov_b64_e32 v[20:21], 0
	v_mov_b64_e32 v[22:23], 0
	v_mov_b64_e32 v[24:25], 0
	v_mov_b64_e32 v[26:27], 0
	v_mov_b64_e32 v[28:29], 0
	v_mov_b64_e32 v[30:31], 0
	v_mov_b64_e32 v[32:33], 0
	v_mov_b64_e32 v[34:35], 0
	v_mov_b64_e32 v[36:37], 0
	v_mov_b64_e32 v[38:39], 0
	v_mov_b64_e32 v[40:41], 0
	v_mov_b64_e32 v[42:43], 0
	v_mov_b64_e32 v[44:45], 0
	v_mov_b64_e32 v[46:47], 0
	v_mov_b64_e32 v[48:49], 0
	v_mov_b64_e32 v[50:51], 0
	v_mov_b64_e32 v[52:53], 0
	v_mov_b64_e32 v[54:55], 0
	v_mov_b64_e32 v[56:57], 0
	v_mov_b64_e32 v[58:59], 0
	v_mov_b64_e32 v[60:61], 0
	v_mov_b64_e32 v[62:63], 0
	v_mov_b64_e32 v[64:65], 0
	v_mov_b64_e32 v[66:67], 0
	v_mov_b64_e32 v[68:69], 0
	v_mov_b64_e32 v[70:71], 0
	v_mov_b64_e32 v[72:73], 0
	v_mov_b64_e32 v[74:75], 0
	v_mov_b64_e32 v[76:77], 0
	v_mov_b64_e32 v[78:79], 0
	v_mov_b64_e32 v[80:81], 0
	v_mov_b64_e32 v[82:83], 0
	v_mov_b64_e32 v[84:85], 0
	v_mov_b64_e32 v[86:87], 0
	v_mov_b64_e32 v[88:89], 0
	v_mov_b64_e32 v[90:91], 0
	v_mov_b64_e32 v[92:93], 0
	v_mov_b64_e32 v[94:95], 0
	v_mov_b64_e32 v[96:97], 0
	v_mov_b64_e32 v[98:99], 0
	v_mov_b64_e32 v[100:101], 0
	v_mov_b64_e32 v[102:103], 0
	v_mov_b64_e32 v[104:105], 0
	v_mov_b64_e32 v[106:107], 0
	v_mov_b64_e32 v[108:109], 0
	v_mov_b64_e32 v[110:111], 0
	v_mov_b64_e32 v[112:113], 0
	v_mov_b64_e32 v[114:115], 0
	v_mov_b64_e32 v[116:117], 0
	v_mov_b64_e32 v[118:119], 0
	v_mov_b64_e32 v[120:121], 0
	v_mov_b64_e32 v[122:123], 0
	v_mov_b64_e32 v[124:125], 0
	v_mov_b64_e32 v[126:127], 0
	s_addc_u32 s91, s63, 0
	s_mov_b32 s62, 0
	.p2alignl 6, 3212836864

.LBB0_504:
	v_mov_b64_e32 v[0:1], 0x3c6
	s_ashr_i32 s65, s64, 31
	v_cmp_lt_i64_e32 vcc, s[8:9], v[0:1]
	s_lshl_b64 s[8:9], s[64:65], 20
	s_add_u32 s66, s27, s8
	s_addc_u32 s67, s74, s9
	s_and_b64 s[8:9], vcc, exec
	s_cselect_b32 s10, s67, s5
	s_cselect_b32 s11, s66, s4
	s_ashr_i32 s63, s62, 31
	s_lshl_b64 s[8:9], s[62:63], 20
	s_add_u32 s68, s75, s8
	s_addc_u32 s69, s76, s9
	s_and_b64 s[8:9], vcc, exec
	s_cselect_b32 s63, s69, s7
	s_cselect_b32 s65, s68, s6
	s_add_u32 s4, s4, 0x80080
	s_addc_u32 s5, s5, 0
	s_add_u32 s70, s6, 0x100
	v_mov_b64_e32 v[0:1], 0
	v_mov_b64_e32 v[2:3], 0
	v_mov_b64_e32 v[4:5], 0
	v_mov_b64_e32 v[6:7], 0
	v_mov_b64_e32 v[8:9], 0
	v_mov_b64_e32 v[10:11], 0
	v_mov_b64_e32 v[12:13], 0
	v_mov_b64_e32 v[14:15], 0
	v_mov_b64_e32 v[16:17], 0
	v_mov_b64_e32 v[18:19], 0
	v_mov_b64_e32 v[20:21], 0
	v_mov_b64_e32 v[22:23], 0
	v_mov_b64_e32 v[24:25], 0
	v_mov_b64_e32 v[26:27], 0
	v_mov_b64_e32 v[28:29], 0
	v_mov_b64_e32 v[30:31], 0
	v_mov_b64_e32 v[32:33], 0
	v_mov_b64_e32 v[34:35], 0
	v_mov_b64_e32 v[36:37], 0
	v_mov_b64_e32 v[38:39], 0
	v_mov_b64_e32 v[40:41], 0
	v_mov_b64_e32 v[42:43], 0
	v_mov_b64_e32 v[44:45], 0
	v_mov_b64_e32 v[46:47], 0
	v_mov_b64_e32 v[48:49], 0
	v_mov_b64_e32 v[50:51], 0
	v_mov_b64_e32 v[52:53], 0
	v_mov_b64_e32 v[54:55], 0
	v_mov_b64_e32 v[56:57], 0
	v_mov_b64_e32 v[58:59], 0
	v_mov_b64_e32 v[60:61], 0
	v_mov_b64_e32 v[62:63], 0
	v_mov_b64_e32 v[64:65], 0
	v_mov_b64_e32 v[66:67], 0
	v_mov_b64_e32 v[68:69], 0
	v_mov_b64_e32 v[70:71], 0
	v_mov_b64_e32 v[72:73], 0
	v_mov_b64_e32 v[74:75], 0
	v_mov_b64_e32 v[76:77], 0
	v_mov_b64_e32 v[78:79], 0
	v_mov_b64_e32 v[80:81], 0
	v_mov_b64_e32 v[82:83], 0
	v_mov_b64_e32 v[84:85], 0
	v_mov_b64_e32 v[86:87], 0
	v_mov_b64_e32 v[88:89], 0
	v_mov_b64_e32 v[90:91], 0
	v_mov_b64_e32 v[92:93], 0
	v_mov_b64_e32 v[94:95], 0
	v_mov_b64_e32 v[96:97], 0
	v_mov_b64_e32 v[98:99], 0
	v_mov_b64_e32 v[100:101], 0
	v_mov_b64_e32 v[102:103], 0
	v_mov_b64_e32 v[104:105], 0
	v_mov_b64_e32 v[106:107], 0
	v_mov_b64_e32 v[108:109], 0
	v_mov_b64_e32 v[110:111], 0
	v_mov_b64_e32 v[112:113], 0
	v_mov_b64_e32 v[114:115], 0
	v_mov_b64_e32 v[116:117], 0
	v_mov_b64_e32 v[118:119], 0
	v_mov_b64_e32 v[120:121], 0
	v_mov_b64_e32 v[122:123], 0
	v_mov_b64_e32 v[124:125], 0
	v_mov_b64_e32 v[126:127], 0
	s_addc_u32 s71, s7, 0
	s_mov_b32 s72, -2
	.p2alignl 6, 3212836864

.LBB0_1113:
	s_add_i32 s85, s76, -2
	s_add_u32 s64, s64, 0x80
	s_addc_u32 s65, s65, 0
	s_add_u32 s91, s66, 0x100
	v_mov_b64_e32 v[0:1], 0
	v_mov_b64_e32 v[2:3], 0
	v_mov_b64_e32 v[4:5], 0
	v_mov_b64_e32 v[6:7], 0
	v_mov_b64_e32 v[8:9], 0
	v_mov_b64_e32 v[10:11], 0
	v_mov_b64_e32 v[12:13], 0
	v_mov_b64_e32 v[14:15], 0
	v_mov_b64_e32 v[16:17], 0
	v_mov_b64_e32 v[18:19], 0
	v_mov_b64_e32 v[20:21], 0
	v_mov_b64_e32 v[22:23], 0
	v_mov_b64_e32 v[24:25], 0
	v_mov_b64_e32 v[26:27], 0
	v_mov_b64_e32 v[28:29], 0
	v_mov_b64_e32 v[30:31], 0
	v_mov_b64_e32 v[32:33], 0
	v_mov_b64_e32 v[34:35], 0
	v_mov_b64_e32 v[36:37], 0
	v_mov_b64_e32 v[38:39], 0
	v_mov_b64_e32 v[40:41], 0
	v_mov_b64_e32 v[42:43], 0
	v_mov_b64_e32 v[44:45], 0
	v_mov_b64_e32 v[46:47], 0
	v_mov_b64_e32 v[48:49], 0
	v_mov_b64_e32 v[50:51], 0
	v_mov_b64_e32 v[52:53], 0
	v_mov_b64_e32 v[54:55], 0
	v_mov_b64_e32 v[56:57], 0
	v_mov_b64_e32 v[58:59], 0
	v_mov_b64_e32 v[60:61], 0
	v_mov_b64_e32 v[62:63], 0
	v_mov_b64_e32 v[64:65], 0
	v_mov_b64_e32 v[66:67], 0
	v_mov_b64_e32 v[68:69], 0
	v_mov_b64_e32 v[70:71], 0
	v_mov_b64_e32 v[72:73], 0
	v_mov_b64_e32 v[74:75], 0
	v_mov_b64_e32 v[76:77], 0
	v_mov_b64_e32 v[78:79], 0
	v_mov_b64_e32 v[80:81], 0
	v_mov_b64_e32 v[82:83], 0
	v_mov_b64_e32 v[84:85], 0
	v_mov_b64_e32 v[86:87], 0
	v_mov_b64_e32 v[88:89], 0
	v_mov_b64_e32 v[90:91], 0
	v_mov_b64_e32 v[92:93], 0
	v_mov_b64_e32 v[94:95], 0
	v_mov_b64_e32 v[96:97], 0
	v_mov_b64_e32 v[98:99], 0
	v_mov_b64_e32 v[100:101], 0
	v_mov_b64_e32 v[102:103], 0
	v_mov_b64_e32 v[104:105], 0
	v_mov_b64_e32 v[106:107], 0
	v_mov_b64_e32 v[108:109], 0
	v_mov_b64_e32 v[110:111], 0
	v_mov_b64_e32 v[112:113], 0
	v_mov_b64_e32 v[114:115], 0
	v_mov_b64_e32 v[116:117], 0
	v_mov_b64_e32 v[118:119], 0
	v_mov_b64_e32 v[120:121], 0
	v_mov_b64_e32 v[122:123], 0
	v_mov_b64_e32 v[124:125], 0
	v_mov_b64_e32 v[126:127], 0
	s_addc_u32 vcc_lo, s67, 0
	s_mov_b32 s66, 0
	.p2alignl 6, 3212836864

.LBB0_1281:
	s_add_i32 s5, s79, -2
	s_add_u32 s58, s58, 0x80
	s_addc_u32 s59, s59, 0
	s_add_u32 s21, s60, 0x100
	v_mov_b64_e32 v[0:1], 0
	v_mov_b64_e32 v[2:3], 0
	v_mov_b64_e32 v[4:5], 0
	v_mov_b64_e32 v[6:7], 0
	v_mov_b64_e32 v[8:9], 0
	v_mov_b64_e32 v[10:11], 0
	v_mov_b64_e32 v[12:13], 0
	v_mov_b64_e32 v[14:15], 0
	v_mov_b64_e32 v[16:17], 0
	v_mov_b64_e32 v[18:19], 0
	v_mov_b64_e32 v[20:21], 0
	v_mov_b64_e32 v[22:23], 0
	v_mov_b64_e32 v[24:25], 0
	v_mov_b64_e32 v[26:27], 0
	v_mov_b64_e32 v[28:29], 0
	v_mov_b64_e32 v[30:31], 0
	v_mov_b64_e32 v[32:33], 0
	v_mov_b64_e32 v[34:35], 0
	v_mov_b64_e32 v[36:37], 0
	v_mov_b64_e32 v[38:39], 0
	v_mov_b64_e32 v[40:41], 0
	v_mov_b64_e32 v[42:43], 0
	v_mov_b64_e32 v[44:45], 0
	v_mov_b64_e32 v[46:47], 0
	v_mov_b64_e32 v[48:49], 0
	v_mov_b64_e32 v[50:51], 0
	v_mov_b64_e32 v[52:53], 0
	v_mov_b64_e32 v[54:55], 0
	v_mov_b64_e32 v[56:57], 0
	v_mov_b64_e32 v[58:59], 0
	v_mov_b64_e32 v[60:61], 0
	v_mov_b64_e32 v[62:63], 0
	v_mov_b64_e32 v[64:65], 0
	v_mov_b64_e32 v[66:67], 0
	v_mov_b64_e32 v[68:69], 0
	v_mov_b64_e32 v[70:71], 0
	v_mov_b64_e32 v[72:73], 0
	v_mov_b64_e32 v[74:75], 0
	v_mov_b64_e32 v[76:77], 0
	v_mov_b64_e32 v[78:79], 0
	v_mov_b64_e32 v[80:81], 0
	v_mov_b64_e32 v[82:83], 0
	v_mov_b64_e32 v[84:85], 0
	v_mov_b64_e32 v[86:87], 0
	v_mov_b64_e32 v[88:89], 0
	v_mov_b64_e32 v[90:91], 0
	v_mov_b64_e32 v[92:93], 0
	v_mov_b64_e32 v[94:95], 0
	v_mov_b64_e32 v[96:97], 0
	v_mov_b64_e32 v[98:99], 0
	v_mov_b64_e32 v[100:101], 0
	v_mov_b64_e32 v[102:103], 0
	v_mov_b64_e32 v[104:105], 0
	v_mov_b64_e32 v[106:107], 0
	v_mov_b64_e32 v[108:109], 0
	v_mov_b64_e32 v[110:111], 0
	v_mov_b64_e32 v[112:113], 0
	v_mov_b64_e32 v[114:115], 0
	v_mov_b64_e32 v[116:117], 0
	v_mov_b64_e32 v[118:119], 0
	v_mov_b64_e32 v[120:121], 0
	v_mov_b64_e32 v[122:123], 0
	v_mov_b64_e32 v[124:125], 0
	v_mov_b64_e32 v[126:127], 0
	s_addc_u32 s80, s61, 0
	s_mov_b32 s60, 0
	s_waitcnt lgkmcnt(0)
	.p2alignl 6, 3212836864

.LBB0_1435:
	s_ashr_i32 s17, s16, 31
	v_cmp_lt_i64_e32 vcc, s[18:19], v[186:187]
	s_lshl_b64 s[18:19], s[16:17], 19
	s_add_u32 s18, s47, s18
	s_addc_u32 s19, s54, s19
	s_and_b64 s[20:21], vcc, exec
	s_cselect_b32 s17, s19, s7
	s_cselect_b32 s66, s18, s6
	s_ashr_i32 s13, s12, 31
	s_lshl_b64 s[20:21], s[12:13], 19
	s_add_u32 s20, s37, s20
	s_addc_u32 s21, s46, s21
	s_and_b64 s[52:53], vcc, exec
	s_cselect_b32 s13, s21, s51
	s_cselect_b32 s67, s20, s50
	s_add_u32 s6, s6, 0x40080
	s_addc_u32 s7, s7, 0
	s_add_u32 s68, s50, 0x100
	v_mov_b64_e32 v[0:1], 0
	v_mov_b64_e32 v[2:3], 0
	v_mov_b64_e32 v[4:5], 0
	v_mov_b64_e32 v[6:7], 0
	v_mov_b64_e32 v[8:9], 0
	v_mov_b64_e32 v[10:11], 0
	v_mov_b64_e32 v[12:13], 0
	v_mov_b64_e32 v[14:15], 0
	v_mov_b64_e32 v[16:17], 0
	v_mov_b64_e32 v[18:19], 0
	v_mov_b64_e32 v[20:21], 0
	v_mov_b64_e32 v[22:23], 0
	v_mov_b64_e32 v[24:25], 0
	v_mov_b64_e32 v[26:27], 0
	v_mov_b64_e32 v[28:29], 0
	v_mov_b64_e32 v[30:31], 0
	v_mov_b64_e32 v[32:33], 0
	v_mov_b64_e32 v[34:35], 0
	v_mov_b64_e32 v[36:37], 0
	v_mov_b64_e32 v[38:39], 0
	v_mov_b64_e32 v[40:41], 0
	v_mov_b64_e32 v[42:43], 0
	v_mov_b64_e32 v[44:45], 0
	v_mov_b64_e32 v[46:47], 0
	v_mov_b64_e32 v[48:49], 0
	v_mov_b64_e32 v[50:51], 0
	v_mov_b64_e32 v[52:53], 0
	v_mov_b64_e32 v[54:55], 0
	v_mov_b64_e32 v[56:57], 0
	v_mov_b64_e32 v[58:59], 0
	v_mov_b64_e32 v[60:61], 0
	v_mov_b64_e32 v[62:63], 0
	v_mov_b64_e32 v[64:65], 0
	v_mov_b64_e32 v[66:67], 0
	v_mov_b64_e32 v[68:69], 0
	v_mov_b64_e32 v[70:71], 0
	v_mov_b64_e32 v[72:73], 0
	v_mov_b64_e32 v[74:75], 0
	v_mov_b64_e32 v[76:77], 0
	v_mov_b64_e32 v[78:79], 0
	v_mov_b64_e32 v[80:81], 0
	v_mov_b64_e32 v[82:83], 0
	v_mov_b64_e32 v[84:85], 0
	v_mov_b64_e32 v[86:87], 0
	v_mov_b64_e32 v[88:89], 0
	v_mov_b64_e32 v[90:91], 0
	v_mov_b64_e32 v[92:93], 0
	v_mov_b64_e32 v[94:95], 0
	v_mov_b64_e32 v[96:97], 0
	v_mov_b64_e32 v[98:99], 0
	v_mov_b64_e32 v[100:101], 0
	v_mov_b64_e32 v[102:103], 0
	v_mov_b64_e32 v[104:105], 0
	v_mov_b64_e32 v[106:107], 0
	v_mov_b64_e32 v[108:109], 0
	v_mov_b64_e32 v[110:111], 0
	v_mov_b64_e32 v[112:113], 0
	v_mov_b64_e32 v[114:115], 0
	v_mov_b64_e32 v[116:117], 0
	v_mov_b64_e32 v[118:119], 0
	v_mov_b64_e32 v[120:121], 0
	v_mov_b64_e32 v[122:123], 0
	v_mov_b64_e32 v[124:125], 0
	v_mov_b64_e32 v[126:127], 0
	s_addc_u32 s69, s51, 0
	s_mov_b32 s70, -2
	.p2alignl 6, 3212836864
